# phase-3 attention loop software-pipelined: next tile QK + LDS fragment reads overlapped with softmax/PV, counted lgkm waits
# speedup vs baseline: 1.0127x; 1.0127x over previous
.LBB0_803:
	ds_write_b128 v105, v[48:51] offset:18432
	v_mov_b64_e32 v[160:161], v[52:53]
	v_mov_b64_e32 v[162:163], v[54:55]
	v_lshlrev_b32_e32 v0, 1, v136
	v_or_b32_e32 v155, 0x1f000, v132
	v_add_u32_e32 v155, v155, v109
	ds_read_b128 v[208:211], v155
	ds_read_b128 v[212:215], v155 offset:32
	ds_read_b128 v[216:219], v155 offset:64
	ds_read_b128 v[220:223], v155 offset:96
	ds_read_b128 v[224:227], v155 offset:4608
	ds_read_b128 v[228:231], v155 offset:4640
	ds_read_b128 v[242:245], v155 offset:4672
	ds_read_b128 v[246:249], v155 offset:4704
	s_waitcnt lgkmcnt(7)
	v_mfma_f32_32x32x16_bf16 v[64:79], v[208:211], v[80:83], 0
	s_waitcnt lgkmcnt(6)
	v_mfma_f32_32x32x16_bf16 v[64:79], v[212:215], v[84:87], v[64:79]
	s_waitcnt lgkmcnt(5)
	v_mfma_f32_32x32x16_bf16 v[64:79], v[216:219], v[88:91], v[64:79]
	s_waitcnt lgkmcnt(4)
	v_mfma_f32_32x32x16_bf16 v[64:79], v[220:223], v[92:95], v[64:79]
	s_waitcnt lgkmcnt(3)
	v_mfma_f32_32x32x16_bf16 v[48:63], v[224:227], v[80:83], 0
	s_waitcnt lgkmcnt(2)
	v_mfma_f32_32x32x16_bf16 v[48:63], v[228:231], v[84:87], v[48:63]
	s_waitcnt lgkmcnt(1)
	v_mfma_f32_32x32x16_bf16 v[48:63], v[242:245], v[88:91], v[48:63]
	s_waitcnt lgkmcnt(0)
	v_mfma_f32_32x32x16_bf16 v[48:63], v[246:249], v[92:95], v[48:63]
	s_waitcnt vmcnt(0) lgkmcnt(0)
	s_barrier
.Lat3_even:
	s_add_i32 s18, s19, 1
	v_max3_f32 v196, v64, v65, v66
	v_max3_f32 v196, v196, v67, v68
	v_max3_f32 v196, v196, v69, v70
	v_max3_f32 v196, v196, v71, v72
	v_max3_f32 v196, v196, v73, v74
	v_max3_f32 v196, v196, v75, v76
	v_max3_f32 v196, v196, v77, v78
	v_max_f32_e32 v196, v196, v79
	v_max3_f32 v197, v48, v49, v50
	v_max3_f32 v197, v197, v51, v52
	v_max3_f32 v197, v197, v53, v54
	v_max3_f32 v197, v197, v55, v56
	v_max3_f32 v197, v197, v57, v58
	v_max3_f32 v197, v197, v59, v60
	v_max3_f32 v197, v197, v61, v62
	v_max_f32_e32 v197, v197, v63
	v_max_f32_e32 v196, v196, v197
	ds_bpermute_b32 v12, v234, v196
	ds_write_b128 v105, v[96:99]
	ds_write_b128 v105, v[160:163] offset:27648
	s_add_i32 s16, s19, 3
	v_min_i32_e32 v14, s16, v133
	v_lshlrev_b32_e32 v6, 6, v14
	v_add_u32_e32 v2, v6, v104
	v_ashrrev_i32_e32 v3, 31, v2
	v_lshlrev_b64 v[2:3], 7, v[2:3]
	v_ashrrev_i32_e32 v7, 31, v6
	v_lshl_add_u64 v[2:3], v[138:139], 0, v[2:3]
	v_lshl_add_u64 v[6:7], v[6:7], 1, v[134:135]
	v_or_b32_e32 v155, 0x23800, v132
	global_load_dwordx4 v[2:5], v[2:3], off
	v_add_u32_e32 v155, v155, v109
	global_load_dwordx4 v[6:9], v[6:7], off
	ds_read_b64 v[158:159], v152
	ds_read_b128 v[208:211], v155
	ds_read_b128 v[212:215], v155 offset:32
	ds_read_b128 v[216:219], v155 offset:64
	ds_read_b128 v[220:223], v155 offset:96
	s_mov_b32 s16, 0x1f000
	v_add3_u32 v13, s16, v109, v0
	v_add_u32_e32 v15, 0x2000, v13
	v_add_u32_e32 v13, 0x3000, v13
	ds_read2_b64 v[224:227], v15 offset0:128 offset1:130
	ds_read2_b64 v[242:245], v13 offset0:192 offset1:194
	ds_read2_b64 v[228:231], v15 offset0:132 offset1:134
	ds_read2_b64 v[246:249], v13 offset0:196 offset1:198
	v_mov_b32_e32 v10, 0
	s_waitcnt lgkmcnt(11)
	v_max3_f32 v12, v154, v196, v12
	v_sub_f32_e32 v232, v154, v12
	v_exp_f32_e32 v232, v232
	v_cmp_neq_f32_e32 vcc, v12, v154
	s_waitcnt lgkmcnt(8)
	v_lshrrev_b32_e32 v158, v136, v158
	v_lshrrev_b32_e32 v159, v136, v159
	s_cbranch_vccz .Lat3_nors_a
	v_pk_mul_f32 v[46:47], v[46:47], v[232:233] op_sel_hi:[1,0]
	v_pk_mul_f32 v[44:45], v[44:45], v[232:233] op_sel_hi:[1,0]
	v_pk_mul_f32 v[42:43], v[42:43], v[232:233] op_sel_hi:[1,0]
	v_pk_mul_f32 v[40:41], v[40:41], v[232:233] op_sel_hi:[1,0]
	v_pk_mul_f32 v[38:39], v[38:39], v[232:233] op_sel_hi:[1,0]
	v_pk_mul_f32 v[36:37], v[36:37], v[232:233] op_sel_hi:[1,0]
	v_pk_mul_f32 v[34:35], v[34:35], v[232:233] op_sel_hi:[1,0]
	v_pk_mul_f32 v[32:33], v[32:33], v[232:233] op_sel_hi:[1,0]
	v_pk_mul_f32 v[30:31], v[30:31], v[232:233] op_sel_hi:[1,0]
	v_pk_mul_f32 v[28:29], v[28:29], v[232:233] op_sel_hi:[1,0]
	v_pk_mul_f32 v[26:27], v[26:27], v[232:233] op_sel_hi:[1,0]
	v_pk_mul_f32 v[24:25], v[24:25], v[232:233] op_sel_hi:[1,0]
	v_pk_mul_f32 v[22:23], v[22:23], v[232:233] op_sel_hi:[1,0]
	v_pk_mul_f32 v[20:21], v[20:21], v[232:233] op_sel_hi:[1,0]
	v_pk_mul_f32 v[18:19], v[18:19], v[232:233] op_sel_hi:[1,0]
	v_pk_mul_f32 v[16:17], v[16:17], v[232:233] op_sel_hi:[1,0]
.Lat3_nors_a:
	v_sub_f32_e32 v64, v64, v12
	v_sub_f32_e32 v65, v65, v12
	v_exp_f32_e32 v64, v64
	v_exp_f32_e32 v65, v65
	v_bfe_i32 v199, v158, 0, 1
	v_bfe_i32 v241, v158, 1, 1
	v_and_b32_e32 v64, v64, v199
	v_and_b32_e32 v65, v65, v241
	v_add_f32_e32 v10, v64, v10
	v_add_f32_e32 v10, v65, v10
	v_cvt_pk_bf16_f32 v200, v64, v65
	s_waitcnt lgkmcnt(7)
	v_mfma_f32_32x32x16_bf16 v[164:179], v[208:211], v[80:83], 0
	v_sub_f32_e32 v66, v66, v12
	v_sub_f32_e32 v67, v67, v12
	v_exp_f32_e32 v66, v66
	v_exp_f32_e32 v67, v67
	v_bfe_i32 v199, v158, 2, 1
	v_bfe_i32 v241, v158, 3, 1
	v_and_b32_e32 v66, v66, v199
	v_and_b32_e32 v67, v67, v241
	v_add_f32_e32 v10, v66, v10
	v_add_f32_e32 v10, v67, v10
	v_cvt_pk_bf16_f32 v201, v66, v67
	s_waitcnt lgkmcnt(6)
	v_mfma_f32_32x32x16_bf16 v[164:179], v[212:215], v[84:87], v[164:179]
	v_sub_f32_e32 v68, v68, v12
	v_sub_f32_e32 v69, v69, v12
	v_exp_f32_e32 v68, v68
	v_exp_f32_e32 v69, v69
	v_bfe_i32 v199, v158, 8, 1
	v_bfe_i32 v241, v158, 9, 1
	v_and_b32_e32 v68, v68, v199
	v_and_b32_e32 v69, v69, v241
	v_add_f32_e32 v10, v68, v10
	v_add_f32_e32 v10, v69, v10
	v_cvt_pk_bf16_f32 v202, v68, v69
	s_waitcnt lgkmcnt(5)
	v_mfma_f32_32x32x16_bf16 v[164:179], v[216:219], v[88:91], v[164:179]
	v_sub_f32_e32 v70, v70, v12
	v_sub_f32_e32 v71, v71, v12
	v_exp_f32_e32 v70, v70
	v_exp_f32_e32 v71, v71
	v_bfe_i32 v199, v158, 10, 1
	v_bfe_i32 v241, v158, 11, 1
	v_and_b32_e32 v70, v70, v199
	v_and_b32_e32 v71, v71, v241
	v_add_f32_e32 v10, v70, v10
	v_add_f32_e32 v10, v71, v10
	v_cvt_pk_bf16_f32 v203, v70, v71
	s_waitcnt lgkmcnt(4)
	v_mfma_f32_32x32x16_bf16 v[164:179], v[220:223], v[92:95], v[164:179]
	ds_read_b128 v[208:211], v155 offset:4608
	ds_read_b128 v[212:215], v155 offset:4640
	ds_read_b128 v[216:219], v155 offset:4672
	ds_read_b128 v[220:223], v155 offset:4704
	v_sub_f32_e32 v72, v72, v12
	v_sub_f32_e32 v73, v73, v12
	v_exp_f32_e32 v72, v72
	v_exp_f32_e32 v73, v73
	v_bfe_i32 v199, v158, 16, 1
	v_bfe_i32 v241, v158, 17, 1
	v_and_b32_e32 v72, v72, v199
	v_and_b32_e32 v73, v73, v241
	v_add_f32_e32 v10, v72, v10
	v_add_f32_e32 v10, v73, v10
	v_cvt_pk_bf16_f32 v204, v72, v73
	s_waitcnt lgkmcnt(7)
	v_mfma_f32_32x32x16_bf16 v[32:47], v[224:227], v[200:203], v[32:47]
	v_sub_f32_e32 v74, v74, v12
	v_sub_f32_e32 v75, v75, v12
	v_exp_f32_e32 v74, v74
	v_exp_f32_e32 v75, v75
	v_bfe_i32 v199, v158, 18, 1
	v_bfe_i32 v241, v158, 19, 1
	v_and_b32_e32 v74, v74, v199
	v_and_b32_e32 v75, v75, v241
	v_add_f32_e32 v10, v74, v10
	v_add_f32_e32 v10, v75, v10
	v_cvt_pk_bf16_f32 v205, v74, v75
	s_waitcnt lgkmcnt(6)
	v_mfma_f32_32x32x16_bf16 v[16:31], v[242:245], v[200:203], v[16:31]
	ds_read2_b64 v[224:227], v15 offset0:136 offset1:138
	ds_read2_b64 v[242:245], v13 offset0:200 offset1:202
	v_sub_f32_e32 v76, v76, v12
	v_sub_f32_e32 v77, v77, v12
	v_exp_f32_e32 v76, v76
	v_exp_f32_e32 v77, v77
	v_bfe_i32 v199, v158, 24, 1
	v_bfe_i32 v241, v158, 25, 1
	v_and_b32_e32 v76, v76, v199
	v_and_b32_e32 v77, v77, v241
	v_add_f32_e32 v10, v76, v10
	v_add_f32_e32 v10, v77, v10
	v_cvt_pk_bf16_f32 v206, v76, v77
	s_waitcnt lgkmcnt(5)
	v_mfma_f32_32x32x16_bf16 v[180:195], v[208:211], v[80:83], 0
	v_sub_f32_e32 v78, v78, v12
	v_sub_f32_e32 v79, v79, v12
	v_exp_f32_e32 v78, v78
	v_exp_f32_e32 v79, v79
	v_bfe_i32 v199, v158, 26, 1
	v_bfe_i32 v241, v158, 27, 1
	v_and_b32_e32 v78, v78, v199
	v_and_b32_e32 v79, v79, v241
	v_add_f32_e32 v10, v78, v10
	v_add_f32_e32 v10, v79, v10
	v_cvt_pk_bf16_f32 v207, v78, v79
	s_waitcnt lgkmcnt(4)
	v_mfma_f32_32x32x16_bf16 v[180:195], v[212:215], v[84:87], v[180:195]
	v_sub_f32_e32 v48, v48, v12
	v_sub_f32_e32 v49, v49, v12
	v_exp_f32_e32 v48, v48
	v_exp_f32_e32 v49, v49
	v_bfe_i32 v199, v159, 0, 1
	v_bfe_i32 v241, v159, 1, 1
	v_and_b32_e32 v48, v48, v199
	v_and_b32_e32 v49, v49, v241
	v_add_f32_e32 v10, v48, v10
	v_add_f32_e32 v10, v49, v10
	v_cvt_pk_bf16_f32 v200, v48, v49
	v_mfma_f32_32x32x16_bf16 v[32:47], v[228:231], v[204:207], v[32:47]
	v_sub_f32_e32 v50, v50, v12
	v_sub_f32_e32 v51, v51, v12
	v_exp_f32_e32 v50, v50
	v_exp_f32_e32 v51, v51
	v_bfe_i32 v199, v159, 2, 1
	v_bfe_i32 v241, v159, 3, 1
	v_and_b32_e32 v50, v50, v199
	v_and_b32_e32 v51, v51, v241
	v_add_f32_e32 v10, v50, v10
	v_add_f32_e32 v10, v51, v10
	v_cvt_pk_bf16_f32 v201, v50, v51
	v_mfma_f32_32x32x16_bf16 v[16:31], v[246:249], v[204:207], v[16:31]
	ds_read2_b64 v[228:231], v15 offset0:140 offset1:142
	ds_read2_b64 v[246:249], v13 offset0:204 offset1:206
	v_sub_f32_e32 v52, v52, v12
	v_sub_f32_e32 v53, v53, v12
	v_exp_f32_e32 v52, v52
	v_exp_f32_e32 v53, v53
	v_bfe_i32 v199, v159, 8, 1
	v_bfe_i32 v241, v159, 9, 1
	v_and_b32_e32 v52, v52, v199
	v_and_b32_e32 v53, v53, v241
	v_add_f32_e32 v10, v52, v10
	v_add_f32_e32 v10, v53, v10
	v_cvt_pk_bf16_f32 v202, v52, v53
	s_waitcnt lgkmcnt(5)
	v_mfma_f32_32x32x16_bf16 v[180:195], v[216:219], v[88:91], v[180:195]
	v_sub_f32_e32 v54, v54, v12
	v_sub_f32_e32 v55, v55, v12
	v_exp_f32_e32 v54, v54
	v_exp_f32_e32 v55, v55
	v_bfe_i32 v199, v159, 10, 1
	v_bfe_i32 v241, v159, 11, 1
	v_and_b32_e32 v54, v54, v199
	v_and_b32_e32 v55, v55, v241
	v_add_f32_e32 v10, v54, v10
	v_add_f32_e32 v10, v55, v10
	v_cvt_pk_bf16_f32 v203, v54, v55
	s_waitcnt lgkmcnt(4)
	v_mfma_f32_32x32x16_bf16 v[180:195], v[220:223], v[92:95], v[180:195]
	v_sub_f32_e32 v56, v56, v12
	v_sub_f32_e32 v57, v57, v12
	v_exp_f32_e32 v56, v56
	v_exp_f32_e32 v57, v57
	v_bfe_i32 v199, v159, 16, 1
	v_bfe_i32 v241, v159, 17, 1
	v_and_b32_e32 v56, v56, v199
	v_and_b32_e32 v57, v57, v241
	v_add_f32_e32 v10, v56, v10
	v_add_f32_e32 v10, v57, v10
	v_cvt_pk_bf16_f32 v204, v56, v57
	s_waitcnt lgkmcnt(3)
	v_mfma_f32_32x32x16_bf16 v[32:47], v[224:227], v[200:203], v[32:47]
	v_sub_f32_e32 v58, v58, v12
	v_sub_f32_e32 v59, v59, v12
	v_exp_f32_e32 v58, v58
	v_exp_f32_e32 v59, v59
	v_bfe_i32 v199, v159, 18, 1
	v_bfe_i32 v241, v159, 19, 1
	v_and_b32_e32 v58, v58, v199
	v_and_b32_e32 v59, v59, v241
	v_add_f32_e32 v10, v58, v10
	v_add_f32_e32 v10, v59, v10
	v_cvt_pk_bf16_f32 v205, v58, v59
	s_waitcnt lgkmcnt(2)
	v_mfma_f32_32x32x16_bf16 v[16:31], v[242:245], v[200:203], v[16:31]
	v_sub_f32_e32 v60, v60, v12
	v_sub_f32_e32 v61, v61, v12
	v_exp_f32_e32 v60, v60
	v_exp_f32_e32 v61, v61
	v_bfe_i32 v199, v159, 24, 1
	v_bfe_i32 v241, v159, 25, 1
	v_and_b32_e32 v60, v60, v199
	v_and_b32_e32 v61, v61, v241
	v_add_f32_e32 v10, v60, v10
	v_add_f32_e32 v10, v61, v10
	v_cvt_pk_bf16_f32 v206, v60, v61
	v_sub_f32_e32 v62, v62, v12
	v_sub_f32_e32 v63, v63, v12
	v_exp_f32_e32 v62, v62
	v_exp_f32_e32 v63, v63
	v_bfe_i32 v199, v159, 26, 1
	v_bfe_i32 v241, v159, 27, 1
	v_and_b32_e32 v62, v62, v199
	v_and_b32_e32 v63, v63, v241
	v_add_f32_e32 v10, v62, v10
	v_add_f32_e32 v10, v63, v10
	v_cvt_pk_bf16_f32 v207, v62, v63
	v_cmp_eq_u32_e32 vcc, s18, v111
	v_add_u32_e32 v152, 8, v152
	v_fmac_f32_e32 v10, v153, v232
	s_waitcnt lgkmcnt(1)
	v_mfma_f32_32x32x16_bf16 v[32:47], v[228:231], v[204:207], v[32:47]
	s_or_b64 s[14:15], vcc, s[14:15]
	s_mov_b32 s19, s18
	v_mov_b32_e32 v154, v12
	v_mov_b32_e32 v153, v10
	s_waitcnt lgkmcnt(0)
	v_mfma_f32_32x32x16_bf16 v[16:31], v[246:249], v[204:207], v[16:31]
	s_waitcnt lgkmcnt(0)
	s_barrier
	s_waitcnt vmcnt(0)
	v_mov_b64_e32 v[160:161], v[100:101]
	v_mov_b64_e32 v[162:163], v[102:103]
	v_mov_b64_e32 v[100:101], v[6:7]
	v_mov_b64_e32 v[102:103], v[8:9]
	v_mov_b64_e32 v[96:97], v[2:3]
	v_mov_b64_e32 v[98:99], v[4:5]
	s_andn2_b64 exec, exec, s[14:15]
	s_cbranch_execz .LBB0_759
.Lat3_odd:
	s_add_i32 s18, s19, 1
	v_max3_f32 v196, v164, v165, v166
	v_max3_f32 v196, v196, v167, v168
	v_max3_f32 v196, v196, v169, v170
	v_max3_f32 v196, v196, v171, v172
	v_max3_f32 v196, v196, v173, v174
	v_max3_f32 v196, v196, v175, v176
	v_max3_f32 v196, v196, v177, v178
	v_max_f32_e32 v196, v196, v179
	v_max3_f32 v197, v180, v181, v182
	v_max3_f32 v197, v197, v183, v184
	v_max3_f32 v197, v197, v185, v186
	v_max3_f32 v197, v197, v187, v188
	v_max3_f32 v197, v197, v189, v190
	v_max3_f32 v197, v197, v191, v192
	v_max3_f32 v197, v197, v193, v194
	v_max_f32_e32 v197, v197, v195
	v_max_f32_e32 v196, v196, v197
	ds_bpermute_b32 v12, v234, v196
	ds_write_b128 v105, v[96:99] offset:18432
	ds_write_b128 v105, v[160:163] offset:9216
	s_add_i32 s16, s19, 3
	v_min_i32_e32 v14, s16, v133
	v_lshlrev_b32_e32 v6, 6, v14
	v_add_u32_e32 v2, v6, v104
	v_ashrrev_i32_e32 v3, 31, v2
	v_lshlrev_b64 v[2:3], 7, v[2:3]
	v_ashrrev_i32_e32 v7, 31, v6
	v_lshl_add_u64 v[2:3], v[138:139], 0, v[2:3]
	v_lshl_add_u64 v[6:7], v[6:7], 1, v[134:135]
	v_or_b32_e32 v155, 0x1f000, v132
	global_load_dwordx4 v[2:5], v[2:3], off
	v_add_u32_e32 v155, v155, v109
	global_load_dwordx4 v[6:9], v[6:7], off
	ds_read_b64 v[158:159], v152
	ds_read_b128 v[208:211], v155
	ds_read_b128 v[212:215], v155 offset:32
	ds_read_b128 v[216:219], v155 offset:64
	ds_read_b128 v[220:223], v155 offset:96
	s_mov_b32 s16, 0x23800
	v_add3_u32 v13, s16, v109, v0
	v_add_u32_e32 v15, 0x2000, v13
	v_add_u32_e32 v13, 0x3000, v13
	ds_read2_b64 v[224:227], v15 offset0:128 offset1:130
	ds_read2_b64 v[242:245], v13 offset0:192 offset1:194
	ds_read2_b64 v[228:231], v15 offset0:132 offset1:134
	ds_read2_b64 v[246:249], v13 offset0:196 offset1:198
	v_mov_b32_e32 v10, 0
	s_waitcnt lgkmcnt(11)
	v_max3_f32 v12, v154, v196, v12
	v_sub_f32_e32 v232, v154, v12
	v_exp_f32_e32 v232, v232
	v_cmp_neq_f32_e32 vcc, v12, v154
	s_waitcnt lgkmcnt(8)
	v_lshrrev_b32_e32 v158, v136, v158
	v_lshrrev_b32_e32 v159, v136, v159
	s_cbranch_vccz .Lat3_nors_b
	v_pk_mul_f32 v[46:47], v[46:47], v[232:233] op_sel_hi:[1,0]
	v_pk_mul_f32 v[44:45], v[44:45], v[232:233] op_sel_hi:[1,0]
	v_pk_mul_f32 v[42:43], v[42:43], v[232:233] op_sel_hi:[1,0]
	v_pk_mul_f32 v[40:41], v[40:41], v[232:233] op_sel_hi:[1,0]
	v_pk_mul_f32 v[38:39], v[38:39], v[232:233] op_sel_hi:[1,0]
	v_pk_mul_f32 v[36:37], v[36:37], v[232:233] op_sel_hi:[1,0]
	v_pk_mul_f32 v[34:35], v[34:35], v[232:233] op_sel_hi:[1,0]
	v_pk_mul_f32 v[32:33], v[32:33], v[232:233] op_sel_hi:[1,0]
	v_pk_mul_f32 v[30:31], v[30:31], v[232:233] op_sel_hi:[1,0]
	v_pk_mul_f32 v[28:29], v[28:29], v[232:233] op_sel_hi:[1,0]
	v_pk_mul_f32 v[26:27], v[26:27], v[232:233] op_sel_hi:[1,0]
	v_pk_mul_f32 v[24:25], v[24:25], v[232:233] op_sel_hi:[1,0]
	v_pk_mul_f32 v[22:23], v[22:23], v[232:233] op_sel_hi:[1,0]
	v_pk_mul_f32 v[20:21], v[20:21], v[232:233] op_sel_hi:[1,0]
	v_pk_mul_f32 v[18:19], v[18:19], v[232:233] op_sel_hi:[1,0]
	v_pk_mul_f32 v[16:17], v[16:17], v[232:233] op_sel_hi:[1,0]
.Lat3_nors_b:
	v_sub_f32_e32 v164, v164, v12
	v_sub_f32_e32 v165, v165, v12
	v_exp_f32_e32 v164, v164
	v_exp_f32_e32 v165, v165
	v_bfe_i32 v199, v158, 0, 1
	v_bfe_i32 v241, v158, 1, 1
	v_and_b32_e32 v164, v164, v199
	v_and_b32_e32 v165, v165, v241
	v_add_f32_e32 v10, v164, v10
	v_add_f32_e32 v10, v165, v10
	v_cvt_pk_bf16_f32 v200, v164, v165
	s_waitcnt lgkmcnt(7)
	v_mfma_f32_32x32x16_bf16 v[64:79], v[208:211], v[80:83], 0
	v_sub_f32_e32 v166, v166, v12
	v_sub_f32_e32 v167, v167, v12
	v_exp_f32_e32 v166, v166
	v_exp_f32_e32 v167, v167
	v_bfe_i32 v199, v158, 2, 1
	v_bfe_i32 v241, v158, 3, 1
	v_and_b32_e32 v166, v166, v199
	v_and_b32_e32 v167, v167, v241
	v_add_f32_e32 v10, v166, v10
	v_add_f32_e32 v10, v167, v10
	v_cvt_pk_bf16_f32 v201, v166, v167
	s_waitcnt lgkmcnt(6)
	v_mfma_f32_32x32x16_bf16 v[64:79], v[212:215], v[84:87], v[64:79]
	v_sub_f32_e32 v168, v168, v12
	v_sub_f32_e32 v169, v169, v12
	v_exp_f32_e32 v168, v168
	v_exp_f32_e32 v169, v169
	v_bfe_i32 v199, v158, 8, 1
	v_bfe_i32 v241, v158, 9, 1
	v_and_b32_e32 v168, v168, v199
	v_and_b32_e32 v169, v169, v241
	v_add_f32_e32 v10, v168, v10
	v_add_f32_e32 v10, v169, v10
	v_cvt_pk_bf16_f32 v202, v168, v169
	s_waitcnt lgkmcnt(5)
	v_mfma_f32_32x32x16_bf16 v[64:79], v[216:219], v[88:91], v[64:79]
	v_sub_f32_e32 v170, v170, v12
	v_sub_f32_e32 v171, v171, v12
	v_exp_f32_e32 v170, v170
	v_exp_f32_e32 v171, v171
	v_bfe_i32 v199, v158, 10, 1
	v_bfe_i32 v241, v158, 11, 1
	v_and_b32_e32 v170, v170, v199
	v_and_b32_e32 v171, v171, v241
	v_add_f32_e32 v10, v170, v10
	v_add_f32_e32 v10, v171, v10
	v_cvt_pk_bf16_f32 v203, v170, v171
	s_waitcnt lgkmcnt(4)
	v_mfma_f32_32x32x16_bf16 v[64:79], v[220:223], v[92:95], v[64:79]
	ds_read_b128 v[208:211], v155 offset:4608
	ds_read_b128 v[212:215], v155 offset:4640
	ds_read_b128 v[216:219], v155 offset:4672
	ds_read_b128 v[220:223], v155 offset:4704
	v_sub_f32_e32 v172, v172, v12
	v_sub_f32_e32 v173, v173, v12
	v_exp_f32_e32 v172, v172
	v_exp_f32_e32 v173, v173
	v_bfe_i32 v199, v158, 16, 1
	v_bfe_i32 v241, v158, 17, 1
	v_and_b32_e32 v172, v172, v199
	v_and_b32_e32 v173, v173, v241
	v_add_f32_e32 v10, v172, v10
	v_add_f32_e32 v10, v173, v10
	v_cvt_pk_bf16_f32 v204, v172, v173
	s_waitcnt lgkmcnt(7)
	v_mfma_f32_32x32x16_bf16 v[32:47], v[224:227], v[200:203], v[32:47]
	v_sub_f32_e32 v174, v174, v12
	v_sub_f32_e32 v175, v175, v12
	v_exp_f32_e32 v174, v174
	v_exp_f32_e32 v175, v175
	v_bfe_i32 v199, v158, 18, 1
	v_bfe_i32 v241, v158, 19, 1
	v_and_b32_e32 v174, v174, v199
	v_and_b32_e32 v175, v175, v241
	v_add_f32_e32 v10, v174, v10
	v_add_f32_e32 v10, v175, v10
	v_cvt_pk_bf16_f32 v205, v174, v175
	s_waitcnt lgkmcnt(6)
	v_mfma_f32_32x32x16_bf16 v[16:31], v[242:245], v[200:203], v[16:31]
	ds_read2_b64 v[224:227], v15 offset0:136 offset1:138
	ds_read2_b64 v[242:245], v13 offset0:200 offset1:202
	v_sub_f32_e32 v176, v176, v12
	v_sub_f32_e32 v177, v177, v12
	v_exp_f32_e32 v176, v176
	v_exp_f32_e32 v177, v177
	v_bfe_i32 v199, v158, 24, 1
	v_bfe_i32 v241, v158, 25, 1
	v_and_b32_e32 v176, v176, v199
	v_and_b32_e32 v177, v177, v241
	v_add_f32_e32 v10, v176, v10
	v_add_f32_e32 v10, v177, v10
	v_cvt_pk_bf16_f32 v206, v176, v177
	s_waitcnt lgkmcnt(5)
	v_mfma_f32_32x32x16_bf16 v[48:63], v[208:211], v[80:83], 0
	v_sub_f32_e32 v178, v178, v12
	v_sub_f32_e32 v179, v179, v12
	v_exp_f32_e32 v178, v178
	v_exp_f32_e32 v179, v179
	v_bfe_i32 v199, v158, 26, 1
	v_bfe_i32 v241, v158, 27, 1
	v_and_b32_e32 v178, v178, v199
	v_and_b32_e32 v179, v179, v241
	v_add_f32_e32 v10, v178, v10
	v_add_f32_e32 v10, v179, v10
	v_cvt_pk_bf16_f32 v207, v178, v179
	s_waitcnt lgkmcnt(4)
	v_mfma_f32_32x32x16_bf16 v[48:63], v[212:215], v[84:87], v[48:63]
	v_sub_f32_e32 v180, v180, v12
	v_sub_f32_e32 v181, v181, v12
	v_exp_f32_e32 v180, v180
	v_exp_f32_e32 v181, v181
	v_bfe_i32 v199, v159, 0, 1
	v_bfe_i32 v241, v159, 1, 1
	v_and_b32_e32 v180, v180, v199
	v_and_b32_e32 v181, v181, v241
	v_add_f32_e32 v10, v180, v10
	v_add_f32_e32 v10, v181, v10
	v_cvt_pk_bf16_f32 v200, v180, v181
	v_mfma_f32_32x32x16_bf16 v[32:47], v[228:231], v[204:207], v[32:47]
	v_sub_f32_e32 v182, v182, v12
	v_sub_f32_e32 v183, v183, v12
	v_exp_f32_e32 v182, v182
	v_exp_f32_e32 v183, v183
	v_bfe_i32 v199, v159, 2, 1
	v_bfe_i32 v241, v159, 3, 1
	v_and_b32_e32 v182, v182, v199
	v_and_b32_e32 v183, v183, v241
	v_add_f32_e32 v10, v182, v10
	v_add_f32_e32 v10, v183, v10
	v_cvt_pk_bf16_f32 v201, v182, v183
	v_mfma_f32_32x32x16_bf16 v[16:31], v[246:249], v[204:207], v[16:31]
	ds_read2_b64 v[228:231], v15 offset0:140 offset1:142
	ds_read2_b64 v[246:249], v13 offset0:204 offset1:206
	v_sub_f32_e32 v184, v184, v12
	v_sub_f32_e32 v185, v185, v12
	v_exp_f32_e32 v184, v184
	v_exp_f32_e32 v185, v185
	v_bfe_i32 v199, v159, 8, 1
	v_bfe_i32 v241, v159, 9, 1
	v_and_b32_e32 v184, v184, v199
	v_and_b32_e32 v185, v185, v241
	v_add_f32_e32 v10, v184, v10
	v_add_f32_e32 v10, v185, v10
	v_cvt_pk_bf16_f32 v202, v184, v185
	s_waitcnt lgkmcnt(5)
	v_mfma_f32_32x32x16_bf16 v[48:63], v[216:219], v[88:91], v[48:63]
	v_sub_f32_e32 v186, v186, v12
	v_sub_f32_e32 v187, v187, v12
	v_exp_f32_e32 v186, v186
	v_exp_f32_e32 v187, v187
	v_bfe_i32 v199, v159, 10, 1
	v_bfe_i32 v241, v159, 11, 1
	v_and_b32_e32 v186, v186, v199
	v_and_b32_e32 v187, v187, v241
	v_add_f32_e32 v10, v186, v10
	v_add_f32_e32 v10, v187, v10
	v_cvt_pk_bf16_f32 v203, v186, v187
	s_waitcnt lgkmcnt(4)
	v_mfma_f32_32x32x16_bf16 v[48:63], v[220:223], v[92:95], v[48:63]
	v_sub_f32_e32 v188, v188, v12
	v_sub_f32_e32 v189, v189, v12
	v_exp_f32_e32 v188, v188
	v_exp_f32_e32 v189, v189
	v_bfe_i32 v199, v159, 16, 1
	v_bfe_i32 v241, v159, 17, 1
	v_and_b32_e32 v188, v188, v199
	v_and_b32_e32 v189, v189, v241
	v_add_f32_e32 v10, v188, v10
	v_add_f32_e32 v10, v189, v10
	v_cvt_pk_bf16_f32 v204, v188, v189
	s_waitcnt lgkmcnt(3)
	v_mfma_f32_32x32x16_bf16 v[32:47], v[224:227], v[200:203], v[32:47]
	v_sub_f32_e32 v190, v190, v12
	v_sub_f32_e32 v191, v191, v12
	v_exp_f32_e32 v190, v190
	v_exp_f32_e32 v191, v191
	v_bfe_i32 v199, v159, 18, 1
	v_bfe_i32 v241, v159, 19, 1
	v_and_b32_e32 v190, v190, v199
	v_and_b32_e32 v191, v191, v241
	v_add_f32_e32 v10, v190, v10
	v_add_f32_e32 v10, v191, v10
	v_cvt_pk_bf16_f32 v205, v190, v191
	s_waitcnt lgkmcnt(2)
	v_mfma_f32_32x32x16_bf16 v[16:31], v[242:245], v[200:203], v[16:31]
	v_sub_f32_e32 v192, v192, v12
	v_sub_f32_e32 v193, v193, v12
	v_exp_f32_e32 v192, v192
	v_exp_f32_e32 v193, v193
	v_bfe_i32 v199, v159, 24, 1
	v_bfe_i32 v241, v159, 25, 1
	v_and_b32_e32 v192, v192, v199
	v_and_b32_e32 v193, v193, v241
	v_add_f32_e32 v10, v192, v10
	v_add_f32_e32 v10, v193, v10
	v_cvt_pk_bf16_f32 v206, v192, v193
	v_sub_f32_e32 v194, v194, v12
	v_sub_f32_e32 v195, v195, v12
	v_exp_f32_e32 v194, v194
	v_exp_f32_e32 v195, v195
	v_bfe_i32 v199, v159, 26, 1
	v_bfe_i32 v241, v159, 27, 1
	v_and_b32_e32 v194, v194, v199
	v_and_b32_e32 v195, v195, v241
	v_add_f32_e32 v10, v194, v10
	v_add_f32_e32 v10, v195, v10
	v_cvt_pk_bf16_f32 v207, v194, v195
	v_cmp_eq_u32_e32 vcc, s18, v111
	v_add_u32_e32 v152, 8, v152
	v_fmac_f32_e32 v10, v153, v232
	s_waitcnt lgkmcnt(1)
	v_mfma_f32_32x32x16_bf16 v[32:47], v[228:231], v[204:207], v[32:47]
	s_or_b64 s[14:15], vcc, s[14:15]
	s_mov_b32 s19, s18
	v_mov_b32_e32 v154, v12
	v_mov_b32_e32 v153, v10
	s_waitcnt lgkmcnt(0)
	v_mfma_f32_32x32x16_bf16 v[16:31], v[246:249], v[204:207], v[16:31]
	s_waitcnt lgkmcnt(0)
	s_barrier
	s_waitcnt vmcnt(0)
	v_mov_b64_e32 v[160:161], v[100:101]
	v_mov_b64_e32 v[162:163], v[102:103]
	v_mov_b64_e32 v[100:101], v[6:7]
	v_mov_b64_e32 v[102:103], v[8:9]
	v_mov_b64_e32 v[96:97], v[2:3]
	v_mov_b64_e32 v[98:99], v[4:5]
	s_andn2_b64 exec, exec, s[14:15]
	s_cbranch_execz .LBB0_759
	s_branch .Lat3_even
